# attention steady-state loops (MLA, NATTEN fixed-shift): packed v_pk_add_f32 / v_pk_mov_b32 beside the MFMAs split into scalar pairs (bit-identical)
# speedup vs baseline: 1.0006x; 1.0006x over previous
.LBB0_1113:
	s_or_b64 exec, exec, s[68:69]
	v_cmp_lt_i32_e32 vcc, s36, v201
	s_mov_b64 s[68:69], -1
	s_and_saveexec_b64 s[36:37], vcc
	s_cbranch_execz .LBB0_1117
	v_cmp_ge_u32_e32 vcc, v178, v205
	v_cmp_lt_u32_e64 s[6:7], v178, v206
	s_and_b64 s[70:71], vcc, s[6:7]
	s_mov_b64 s[68:69], 0
	s_and_saveexec_b64 s[6:7], s[70:71]
	s_cbranch_execz .LBB0_1116
	v_add_u32_e32 v146, v181, v218
	v_add_u32_e32 v147, v181, v219
	v_add_u32_sdwa v150, v181, v208 dst_sel:DWORD dst_unused:UNUSED_PAD src0_sel:DWORD src1_sel:BYTE_2
	v_add_u32_sdwa v153, v181, v209 dst_sel:DWORD dst_unused:UNUSED_PAD src0_sel:DWORD src1_sel:BYTE_3
	v_add_u32_sdwa v157, v181, v211 dst_sel:DWORD dst_unused:UNUSED_PAD src0_sel:DWORD src1_sel:BYTE_1
	v_add_u32_sdwa v161, v181, v211 dst_sel:DWORD dst_unused:UNUSED_PAD src0_sel:DWORD src1_sel:BYTE_3
	ds_read_b32 v146, v146 offset:45952
	ds_read_b32 v148, v147 offset:45952
	ds_read_b32 v150, v150 offset:45952
	ds_read_b32 v153, v153 offset:45952
	ds_read_b32 v157, v157 offset:45952
	ds_read_b32 v161, v161 offset:45952
	v_add_u32_sdwa v147, v181, v208 dst_sel:DWORD dst_unused:UNUSED_PAD src0_sel:DWORD src1_sel:BYTE_1
	v_add_u32_sdwa v151, v181, v209 dst_sel:DWORD dst_unused:UNUSED_PAD src0_sel:DWORD src1_sel:BYTE_2
	v_add_u32_e32 v154, v181, v220
	v_add_u32_sdwa v158, v181, v210 dst_sel:DWORD dst_unused:UNUSED_PAD src0_sel:DWORD src1_sel:BYTE_2
	v_add_u32_e32 v177, v181, v222
	ds_read_b32 v147, v147 offset:45952
	ds_read_b32 v152, v151 offset:45952
	ds_read_b32 v154, v154 offset:45952
	ds_read_b32 v158, v158 offset:45952
	ds_read_b32 v178, v177 offset:45952
	v_add_u32_sdwa v149, v181, v209 dst_sel:DWORD dst_unused:UNUSED_PAD src0_sel:DWORD src1_sel:BYTE_1
	v_add_u32_sdwa v151, v181, v208 dst_sel:DWORD dst_unused:UNUSED_PAD src0_sel:DWORD src1_sel:BYTE_3
	v_add_u32_e32 v155, v181, v221
	v_add_u32_sdwa v159, v181, v211 dst_sel:DWORD dst_unused:UNUSED_PAD src0_sel:DWORD src1_sel:BYTE_2
	v_add_u32_e32 v177, v181, v223
	ds_read_b32 v149, v149 offset:45952
	ds_read_b32 v151, v151 offset:45952
	ds_read_b32 v156, v155 offset:45952
	ds_read_b32 v160, v159 offset:45952
	ds_read_b32 v182, v177 offset:45952
	v_add_u32_sdwa v155, v181, v210 dst_sel:DWORD dst_unused:UNUSED_PAD src0_sel:DWORD src1_sel:BYTE_1
	v_add_u32_sdwa v159, v181, v210 dst_sel:DWORD dst_unused:UNUSED_PAD src0_sel:DWORD src1_sel:BYTE_3
	v_add_u32_sdwa v177, v181, v212 dst_sel:DWORD dst_unused:UNUSED_PAD src0_sel:DWORD src1_sel:BYTE_1
	ds_read_b32 v155, v155 offset:45952
	ds_read_b32 v159, v159 offset:45952
	ds_read_b32 v179, v177 offset:45952
	v_add_u32_sdwa v177, v181, v213 dst_sel:DWORD dst_unused:UNUSED_PAD src0_sel:DWORD src1_sel:BYTE_1
	ds_read_b32 v183, v177 offset:45952
	v_add_u32_sdwa v177, v181, v212 dst_sel:DWORD dst_unused:UNUSED_PAD src0_sel:DWORD src1_sel:BYTE_2
	ds_read_b32 v184, v177 offset:45952
	v_add_u32_sdwa v177, v181, v213 dst_sel:DWORD dst_unused:UNUSED_PAD src0_sel:DWORD src1_sel:BYTE_2
	ds_read_b32 v186, v177 offset:45952
	v_add_u32_sdwa v177, v181, v212 dst_sel:DWORD dst_unused:UNUSED_PAD src0_sel:DWORD src1_sel:BYTE_3
	ds_read_b32 v185, v177 offset:45952
	v_add_u32_sdwa v177, v181, v213 dst_sel:DWORD dst_unused:UNUSED_PAD src0_sel:DWORD src1_sel:BYTE_3
	ds_read_b32 v187, v177 offset:45952
	v_add_u32_e32 v177, v181, v224
	ds_read_b32 v188, v177 offset:45952
	v_add_u32_e32 v177, v181, v225
	ds_read_b32 v190, v177 offset:45952
	v_add_u32_sdwa v177, v181, v214 dst_sel:DWORD dst_unused:UNUSED_PAD src0_sel:DWORD src1_sel:BYTE_1
	ds_read_b32 v189, v177 offset:45952
	v_add_u32_sdwa v177, v181, v215 dst_sel:DWORD dst_unused:UNUSED_PAD src0_sel:DWORD src1_sel:BYTE_1
	ds_read_b32 v191, v177 offset:45952
	v_add_u32_sdwa v177, v181, v214 dst_sel:DWORD dst_unused:UNUSED_PAD src0_sel:DWORD src1_sel:BYTE_2
	ds_read_b32 v192, v177 offset:45952
	v_add_u32_sdwa v177, v181, v215 dst_sel:DWORD dst_unused:UNUSED_PAD src0_sel:DWORD src1_sel:BYTE_2
	ds_read_b32 v194, v177 offset:45952
	v_add_u32_sdwa v177, v181, v214 dst_sel:DWORD dst_unused:UNUSED_PAD src0_sel:DWORD src1_sel:BYTE_3
	s_waitcnt lgkmcnt(0)
	v_add_f32_e32 v96, v96, v146
	v_add_f32_e32 v97, v97, v147
	v_add_u32_sdwa v146, v181, v215 dst_sel:DWORD dst_unused:UNUSED_PAD src0_sel:DWORD src1_sel:BYTE_3
	ds_read_b32 v193, v177 offset:45952
	ds_read_b32 v195, v146 offset:45952
	v_add_f32_e32 v108, v108, v188
	v_add_f32_e32 v109, v109, v189
	v_add_f32_e32 v106, v106, v184
	v_add_f32_e32 v107, v107, v185
	v_add_f32_e32 v104, v104, v178
	v_add_f32_e32 v105, v105, v179
	s_waitcnt lgkmcnt(0)
	v_add_f32_e32 v110, v110, v192
	v_add_f32_e32 v111, v111, v193
	v_add_f32_e32 v102, v102, v158
	v_add_f32_e32 v103, v103, v159
	v_add_f32_e32 v100, v100, v154
	v_add_f32_e32 v101, v101, v155
	v_add_f32_e32 v98, v98, v150
	v_add_f32_e32 v99, v99, v151
	v_add_f32_e32 v94, v94, v194
	v_add_f32_e32 v95, v95, v195
	v_add_f32_e32 v92, v92, v190
	v_add_f32_e32 v93, v93, v191
	v_add_f32_e32 v90, v90, v186
	v_add_f32_e32 v91, v91, v187
	v_add_f32_e32 v88, v88, v182
	v_add_f32_e32 v89, v89, v183
	v_add_f32_e32 v86, v86, v160
	v_add_f32_e32 v87, v87, v161
	v_add_f32_e32 v84, v84, v156
	v_add_f32_e32 v85, v85, v157
	v_add_f32_e32 v82, v82, v152
	v_add_f32_e32 v83, v83, v153
	v_add_f32_e32 v80, v80, v148
	v_add_f32_e32 v81, v81, v149
	s_mov_b64 s[68:69], exec

.LBB0_1117:
	s_or_b64 exec, exec, s[36:37]
	s_and_saveexec_b64 s[6:7], s[68:69]
	s_cbranch_execz .LBB0_1106
	v_exp_f32_e32 v146, v96
	v_exp_f32_e32 v96, v80
	v_exp_f32_e32 v147, v97
	v_exp_f32_e32 v97, v81
	v_exp_f32_e32 v148, v98
	v_exp_f32_e32 v98, v82
	v_exp_f32_e32 v149, v99
	v_exp_f32_e32 v99, v83
	v_exp_f32_e32 v150, v100
	v_exp_f32_e32 v100, v84
	v_exp_f32_e32 v151, v101
	v_exp_f32_e32 v101, v85
	v_exp_f32_e32 v152, v102
	v_exp_f32_e32 v102, v86
	v_exp_f32_e32 v153, v103
	v_exp_f32_e32 v103, v87
	v_exp_f32_e32 v104, v104
	v_exp_f32_e32 v80, v88
	v_exp_f32_e32 v105, v105
	v_exp_f32_e32 v81, v89
	v_exp_f32_e32 v88, v106
	v_exp_f32_e32 v82, v90
	v_exp_f32_e32 v89, v107
	v_exp_f32_e32 v83, v91
	v_exp_f32_e32 v90, v108
	v_exp_f32_e32 v84, v92
	v_exp_f32_e32 v91, v109
	v_exp_f32_e32 v85, v93
	v_exp_f32_e32 v110, v110
	v_exp_f32_e32 v86, v94
	v_exp_f32_e32 v111, v111
	v_exp_f32_e32 v87, v95
	v_add_f32_e32 v158, v148, v98
	v_add_f32_e32 v159, v149, v99
	v_add_f32_e32 v160, v146, v96
	v_add_f32_e32 v161, v147, v97
	v_add_f32_e32 v154, v152, v102
	v_add_f32_e32 v155, v153, v103
	v_add_f32_e32 v156, v150, v100
	v_add_f32_e32 v157, v151, v101
	v_mov_b32_e32 v178, v161
	v_mov_b32_e32 v179, v158
	v_mov_b32_e32 v161, v159
	v_add_f32_e32 v158, v178, v160
	v_add_f32_e32 v159, v179, v161
	v_mov_b32_e32 v160, v157
	v_mov_b32_e32 v161, v154
	v_mov_b32_e32 v157, v155
	v_add_f32_e32 v154, v160, v156
	v_add_f32_e32 v155, v161, v157
	v_add_f32_e32 v92, v110, v86
	v_add_f32_e32 v93, v111, v87
	v_add_f32_e32 v94, v90, v84
	v_add_f32_e32 v95, v91, v85
	v_add_f32_e32 v106, v88, v82
	v_add_f32_e32 v107, v89, v83
	v_add_f32_e32 v108, v104, v80
	v_add_f32_e32 v109, v105, v81
	v_add_f32_e32 v159, v158, v159
	v_add_f32_e32 v158, v158, v158
	v_add_f32_e32 v155, v154, v155
	v_add_f32_e32 v154, v154, v154
	v_add_f32_e32 v109, v108, v109
	v_add_f32_e32 v107, v106, v107
	v_mov_b32_e32 v108, v94
	v_mov_b32_e32 v106, v95
	v_mov_b32_e32 v158, v92
	v_mov_b32_e32 v154, v93
	v_add_f32_e32 v94, v108, v106
	v_add_f32_e32 v95, v109, v107
	v_add_f32_e32 v92, v158, v154
	v_add_f32_e32 v93, v159, v155
	s_and_b64 s[2:3], s[2:3], exec
	v_add_f32_e32 v92, v94, v92
	v_add_f32_e32 v93, v95, v93
	s_cselect_b32 s2, 0x2400, 0
	v_add_f32_e32 v92, v92, v93
	v_add_u32_e32 v93, s2, v217
	v_cvt_pk_bf16_f32 v106, v146, v147
	v_cvt_pk_bf16_f32 v107, v148, v149
	v_cvt_pk_bf16_f32 v108, v150, v151
	v_cvt_pk_bf16_f32 v109, v152, v153
	ds_read_b64_tr_b16 v[146:147], v93 offset:26624
	ds_read_b64_tr_b16 v[148:149], v93 offset:27776
	ds_read_b64_tr_b16 v[150:151], v93 offset:26688
	ds_read_b64_tr_b16 v[152:153], v93 offset:27840
	s_waitcnt lgkmcnt(0)
	v_mfma_f32_32x32x16_bf16 v[0:15], v[146:149], v[106:109], v[0:15]
	v_cvt_pk_bf16_f32 v104, v104, v105
	v_cvt_pk_bf16_f32 v105, v88, v89
	v_cvt_pk_bf16_f32 v80, v80, v81
	v_cvt_pk_bf16_f32 v81, v82, v83
	v_cvt_pk_bf16_f32 v82, v84, v85
	v_cvt_pk_bf16_f32 v83, v86, v87
	v_add_f32_e32 v143, v143, v92
	v_mfma_f32_32x32x16_bf16 v[32:47], v[150:153], v[106:109], v[32:47]
	v_cvt_pk_bf16_f32 v106, v90, v91
	v_cvt_pk_bf16_f32 v107, v110, v111
	ds_read_b64_tr_b16 v[88:89], v93 offset:28928
	ds_read_b64_tr_b16 v[90:91], v93 offset:30080
	ds_read_b64_tr_b16 v[108:109], v93 offset:28992
	ds_read_b64_tr_b16 v[110:111], v93 offset:30144
	s_waitcnt lgkmcnt(0)
	v_mfma_f32_32x32x16_bf16 v[0:15], v[88:91], v[104:107], v[0:15]
	v_cvt_pk_bf16_f32 v88, v96, v97
	v_cvt_pk_bf16_f32 v89, v98, v99
	v_cvt_pk_bf16_f32 v90, v100, v101
	ds_read_b64_tr_b16 v[94:95], v93 offset:31232
	ds_read_b64_tr_b16 v[96:97], v93 offset:32384
	ds_read_b64_tr_b16 v[98:99], v93 offset:31296
	ds_read_b64_tr_b16 v[100:101], v93 offset:32448
	v_cvt_pk_bf16_f32 v91, v102, v103
	v_mfma_f32_32x32x16_bf16 v[32:47], v[108:111], v[104:107], v[32:47]
	s_waitcnt lgkmcnt(0)
	v_mfma_f32_32x32x16_bf16 v[0:15], v[94:97], v[88:91], v[0:15]
	v_mfma_f32_32x32x16_bf16 v[32:47], v[98:101], v[88:91], v[32:47]
	ds_read_b64_tr_b16 v[84:85], v93 offset:33536
	ds_read_b64_tr_b16 v[86:87], v93 offset:34688
	ds_read_b64_tr_b16 v[88:89], v93 offset:33600
	ds_read_b64_tr_b16 v[90:91], v93 offset:34752
	s_waitcnt lgkmcnt(0)
	v_mfma_f32_32x32x16_bf16 v[0:15], v[84:87], v[80:83], v[0:15]
	v_mfma_f32_32x32x16_bf16 v[32:47], v[88:91], v[80:83], v[32:47]
	s_branch .LBB0_1106

.LBB0_1187:
	s_or_b64 exec, exec, s[36:37]
	s_add_i32 s34, s34, 1
	s_bitcmp1_b32 s34, 0
	s_cselect_b32 s36, 0x3400, 0
	v_add_u32_e32 v112, s36, v180
	ds_read_b128 v[132:135], v112
	ds_read_b128 v[136:139], v112 offset:32
	v_exp_f32_e32 v174, v48
	v_exp_f32_e32 v175, v49
	v_exp_f32_e32 v182, v50
	s_waitcnt lgkmcnt(0)
	v_mfma_f32_32x32x16_bf16 v[80:95], v[132:135], v[100:103], v[32:47]
	v_exp_f32_e32 v183, v51
	v_exp_f32_e32 v184, v52
	v_exp_f32_e32 v185, v53
	v_exp_f32_e32 v186, v54
	v_exp_f32_e32 v187, v55
	v_exp_f32_e32 v188, v56
	v_exp_f32_e32 v189, v57
	v_mfma_f32_32x32x16_bf16 v[80:95], v[136:139], v[104:107], v[80:95]
	ds_read_b128 v[132:135], v112 offset:64
	ds_read_b128 v[136:139], v112 offset:96
	v_exp_f32_e32 v190, v58
	v_exp_f32_e32 v191, v59
	v_exp_f32_e32 v192, v60
	v_exp_f32_e32 v193, v61
	v_exp_f32_e32 v194, v62
	v_exp_f32_e32 v195, v63
	s_waitcnt lgkmcnt(0)
	v_mfma_f32_32x32x16_bf16 v[80:95], v[132:135], v[108:111], v[80:95]
	ds_read_b128 v[132:135], v112 offset:128
	ds_read_b128 v[48:51], v112 offset:160
	s_and_b64 s[18:19], s[18:19], exec
	s_cselect_b32 s18, 0x2400, 0
	v_exp_f32_e32 v198, v64
	v_exp_f32_e32 v199, v65
	v_exp_f32_e32 v200, v70
	v_mfma_f32_32x32x16_bf16 v[80:95], v[136:139], v[116:119], v[80:95]
	v_exp_f32_e32 v201, v71
	v_exp_f32_e32 v202, v72
	v_exp_f32_e32 v203, v73
	v_exp_f32_e32 v76, v76
	v_cvt_pk_bf16_f32 v71, v200, v201
	v_exp_f32_e32 v78, v78
	v_exp_f32_e32 v79, v79
	s_waitcnt lgkmcnt(0)
	v_mfma_f32_32x32x16_bf16 v[80:95], v[132:135], v[120:123], v[80:95]
	ds_read_b128 v[132:135], v112 offset:6656
	ds_read_b128 v[146:149], v112 offset:6688
	v_exp_f32_e32 v77, v77
	v_cmp_eq_u32_e32 vcc, s34, v173
	v_lshl_add_u64 v[142:143], v[142:143], 0, s[24:25]
	v_lshl_add_u64 v[162:163], v[162:163], 0, s[24:25]
	s_or_b64 s[2:3], vcc, s[2:3]
	v_mfma_f32_32x32x16_bf16 v[80:95], v[48:51], v[96:99], v[80:95]
	s_waitcnt lgkmcnt(0)
	v_mfma_f32_32x32x16_bf16 v[48:63], v[132:135], v[100:103], v[32:47]
	global_load_dwordx4 v[132:135], v[164:165], off
	ds_read_b128 v[150:153], v112 offset:6720
	ds_read_b128 v[154:157], v112 offset:6752
	ds_read_b128 v[158:161], v112 offset:6784
	ds_read_b128 v[136:139], v112 offset:6816
	v_add_u32_e32 v112, s18, v179
	v_lshl_add_u64 v[164:165], v[164:165], 0, s[0:1]
	v_mfma_f32_32x32x16_bf16 v[48:63], v[146:149], v[104:107], v[48:63]
	v_exp_f32_e32 v146, v66
	v_exp_f32_e32 v147, v67
	v_exp_f32_e32 v148, v68
	v_exp_f32_e32 v149, v69
	ds_read_b64_tr_b16 v[64:65], v112 offset:26624
	ds_read_b64_tr_b16 v[66:67], v112 offset:27776
	v_cvt_pk_bf16_f32 v68, v198, v199
	v_cvt_pk_bf16_f32 v69, v146, v147
	s_waitcnt lgkmcnt(0)
	v_mfma_f32_32x32x16_bf16 v[48:63], v[150:153], v[108:111], v[48:63]
	v_exp_f32_e32 v150, v74
	v_exp_f32_e32 v151, v75
	ds_read_b64_tr_b16 v[74:75], v112 offset:27840
	ds_read_b64_tr_b16 v[72:73], v112 offset:26688
	v_cvt_pk_bf16_f32 v70, v148, v149
	v_add_f32_e32 v146, v182, v146
	v_add_f32_e32 v147, v183, v147
	v_add_f32_e32 v198, v174, v198
	v_add_f32_e32 v199, v175, v199
	v_add_f32_e32 v148, v184, v148
	v_add_f32_e32 v149, v185, v149
	v_mfma_f32_32x32x16_bf16 v[0:15], v[64:67], v[68:71], v[0:15]
	ds_read_b64_tr_b16 v[64:65], v112 offset:28928
	ds_read_b64_tr_b16 v[66:67], v112 offset:30080
	v_add_f32_e64 v152, v194, v78
	v_add_f32_e64 v153, v195, v79
	s_waitcnt lgkmcnt(0)
	v_mfma_f32_32x32x16_bf16 v[16:31], v[72:75], v[68:71], v[16:31]
	ds_read_b64_tr_b16 v[74:75], v112 offset:30144
	ds_read_b64_tr_b16 v[72:73], v112 offset:28992
	v_cvt_pk_bf16_f32 v68, v202, v203
	v_cvt_pk_bf16_f32 v69, v150, v151
	v_cvt_pk_bf16_f32 v70, v76, v77
	v_cvt_pk_bf16_f32 v71, v78, v79
	v_mfma_f32_32x32x16_bf16 v[48:63], v[154:157], v[116:119], v[48:63]
	v_add_f32_e64 v154, v192, v76
	v_add_f32_e64 v155, v193, v77
	v_add_f32_e64 v156, v190, v150
	v_add_f32_e64 v157, v191, v151
	v_mfma_f32_32x32x16_bf16 v[0:15], v[64:67], v[68:71], v[0:15]
	s_waitcnt lgkmcnt(0)
	v_mfma_f32_32x32x16_bf16 v[16:31], v[72:75], v[68:71], v[16:31]
	v_cvt_pk_bf16_f32 v68, v174, v175
	v_cvt_pk_bf16_f32 v69, v182, v183
	v_cvt_pk_bf16_f32 v70, v184, v185
	v_cvt_pk_bf16_f32 v71, v186, v187
	v_mfma_f32_32x32x16_bf16 v[48:63], v[158:161], v[120:123], v[48:63]
	v_add_f32_e64 v160, v186, v200
	v_add_f32_e64 v161, v187, v201
	v_mov_b32_e32 v200, v199
	v_mov_b32_e32 v201, v146
	v_mov_b32_e32 v199, v147
	v_add_f32_e32 v64, v200, v198
	v_add_f32_e32 v65, v201, v199
	v_mov_b32_e32 v78, v149
	v_mov_b32_e32 v79, v160
	v_add_f32_e32 v76, v64, v64
	v_add_f32_e32 v77, v64, v65
	ds_read_b64_tr_b16 v[64:65], v112 offset:31232
	ds_read_b64_tr_b16 v[66:67], v112 offset:32384
	ds_read_b64_tr_b16 v[74:75], v112 offset:32448
	ds_read_b64_tr_b16 v[72:73], v112 offset:31296
	s_waitcnt lgkmcnt(0)
	v_mfma_f32_32x32x16_bf16 v[0:15], v[64:67], v[68:71], v[0:15]
	ds_read_b64_tr_b16 v[64:65], v112 offset:33536
	ds_read_b64_tr_b16 v[66:67], v112 offset:34688
	v_mov_b32_e32 v149, v161
	v_add_f32_e64 v78, v78, v148
	v_add_f32_e64 v79, v79, v149
	v_add_f32_e32 v158, v188, v202
	v_add_f32_e32 v159, v189, v203
	v_add_f32_e32 v79, v78, v79
	v_add_f32_e32 v78, v78, v78
	v_add_f32_e32 v147, v158, v159
	v_add_f32_e32 v149, v156, v157
	v_mfma_f32_32x32x16_bf16 v[16:31], v[72:75], v[68:71], v[16:31]
	ds_read_b64_tr_b16 v[74:75], v112 offset:34752
	ds_read_b64_tr_b16 v[72:73], v112 offset:33600
	v_cvt_pk_bf16_f32 v68, v188, v189
	v_cvt_pk_bf16_f32 v69, v190, v191
	v_cvt_pk_bf16_f32 v70, v192, v193
	v_cvt_pk_bf16_f32 v71, v194, v195
	v_mov_b32_e32 v146, v154
	v_mov_b32_e32 v148, v155
	s_waitcnt lgkmcnt(0)
	v_mfma_f32_32x32x16_bf16 v[0:15], v[64:67], v[68:71], v[0:15]
	v_mov_b32_e32 v76, v152
	v_mov_b32_e32 v78, v153
	v_add_f32_e64 v146, v146, v148
	v_add_f32_e64 v147, v147, v149
	v_add_f32_e64 v64, v76, v78
	v_add_f32_e64 v65, v77, v79
	v_add_f32_e32 v64, v146, v64
	v_add_f32_e32 v65, v147, v65
	s_barrier
	v_mfma_f32_32x32x16_bf16 v[16:31], v[72:75], v[68:71], v[16:31]
	v_add_f32_e32 v64, v64, v65
	v_add_f32_e32 v114, v114, v64
	v_mov_b64_e32 v[64:65], v[80:81]
	v_mov_b64_e32 v[66:67], v[82:83]
	v_mov_b64_e32 v[68:69], v[84:85]
	v_mov_b64_e32 v[70:71], v[86:87]
	v_mov_b64_e32 v[72:73], v[88:89]
	v_mfma_f32_32x32x16_bf16 v[48:63], v[136:139], v[96:99], v[48:63]
	v_mov_b64_e32 v[74:75], v[90:91]
	v_mov_b64_e32 v[76:77], v[92:93]
	v_mov_b64_e32 v[78:79], v[94:95]
	s_andn2_b64 exec, exec, s[2:3]
	s_cbranch_execz .LBB0_1192
